# indexer: relu/weighted-sum VALU of each head interleaved two MFMAs behind the second-half MFMA chain (MFMA-VALU overlap within the wave)
# baseline (speedup 1.0000x reference)
; #define LAS __attribute__((address_space(3)))
; #define GAS __attribute__((address_space(1)))
; __device__ __forceinline__ void select_unit(LAS unsigned char* lds, const GAS bf16_t* __restrict__ HA, const GAS float* __restrict__ IW, int b, int qc, GAS float* __restrict__ scr, GAS unsigned long long* __restrict__ MB) {
;     ...
;             for (int i = 0; i < 8; ++i) {
;                 const int kbl = (wid >> 2) + 2 * i, kb = c * 16 + kbl;
;                 if (kb < nkb) {
;                     const LAS bf16_t* kp = Kc + (kbl * 16 + c16) * 72 + lg * 8;
;                     const bf16x8 k0 = *(const LAS bf16x8*)kp, k1 = *(const LAS bf16x8*)(kp + 32);
;                     f32x4 sc = (f32x4){0.f, 0.f, 0.f, 0.f};
; #pragma unroll
;                     for (int hh = 0; hh < 8; ++hh) {
;                         f32x4 acc = __builtin_amdgcn_mfma_f32_16x16x32_bf16(k0, iqf[hh][0], (f32x4){0.f, 0.f, 0.f, 0.f}, 0, 0, 0);
;                         acc = __builtin_amdgcn_mfma_f32_16x16x32_bf16(k1, iqf[hh][1], acc, 0, 0, 0);
; #pragma unroll
;                         for (int r = 0; r < 4; ++r) sc[r] += iwv[hh] * fmaxf(acc[r], 0.f);
;                     }
;                     *(GAS f32x4*)(scr + (size_t)ql * SEQ + kb * 16 + 4 * lg) = sc;
;                 }
.LBB0_360:
	s_cmp_ge_i32 s13, s7
	s_cbranch_scc1 .LBB0_362
	ds_read_b128 v[94:97], v119
	ds_read_b128 v[90:93], v119 offset:64
	s_waitcnt lgkmcnt(1)
	v_mfma_f32_16x16x32_bf16 v[148:151], v[94:97], v[82:85], 0
	v_mfma_f32_16x16x32_bf16 v[156:159], v[94:97], v[30:33], 0
	v_mfma_f32_16x16x32_bf16 v[172:175], v[94:97], v[38:41], 0
	v_mfma_f32_16x16x32_bf16 v[182:185], v[94:97], v[46:49], 0
	v_mfma_f32_16x16x32_bf16 v[186:189], v[94:97], v[54:57], 0
	v_mfma_f32_16x16x32_bf16 v[190:193], v[94:97], v[62:65], 0
	v_mfma_f32_16x16x32_bf16 v[198:201], v[94:97], v[70:73], 0
	v_mfma_f32_16x16x32_bf16 v[202:205], v[94:97], v[78:81], 0
	s_waitcnt lgkmcnt(0)
	v_mfma_f32_16x16x32_bf16 v[148:151], v[90:93], v[26:29], v[148:151]
	v_mfma_f32_16x16x32_bf16 v[156:159], v[90:93], v[34:37], v[156:159]
	s_add_i32 s14, s10, s12
	s_ashr_i32 s15, s14, 31
	v_lshl_add_u64 v[114:115], s[14:15], 2, v[100:101]
	v_mfma_f32_16x16x32_bf16 v[172:175], v[90:93], v[42:45], v[172:175]
	v_max_f32_e32 v148, 0, v148
	v_max_f32_e32 v149, 0, v149
	v_max_f32_e32 v150, 0, v150
	v_max_f32_e32 v151, 0, v151
	v_fma_f32 v110, v102, v148, 0
	v_fma_f32 v111, v103, v149, 0
	v_fma_f32 v112, v102, v150, 0
	v_fma_f32 v113, v103, v151, 0
	v_mfma_f32_16x16x32_bf16 v[182:185], v[90:93], v[50:53], v[182:185]
	v_max_f32_e32 v156, 0, v156
	v_max_f32_e32 v157, 0, v157
	v_max_f32_e32 v158, 0, v158
	v_max_f32_e32 v159, 0, v159
	v_fmac_f32_e32 v110, v22, v156
	v_fmac_f32_e32 v111, v23, v157
	v_fmac_f32_e32 v112, v22, v158
	v_fmac_f32_e32 v113, v23, v159
	v_mfma_f32_16x16x32_bf16 v[186:189], v[90:93], v[58:61], v[186:189]
	v_max_f32_e32 v172, 0, v172
	v_max_f32_e32 v173, 0, v173
	v_max_f32_e32 v174, 0, v174
	v_max_f32_e32 v175, 0, v175
	v_fmac_f32_e32 v110, v104, v172
	v_fmac_f32_e32 v111, v105, v173
	v_fmac_f32_e32 v112, v104, v174
	v_fmac_f32_e32 v113, v105, v175
	v_mfma_f32_16x16x32_bf16 v[190:193], v[90:93], v[66:69], v[190:193]
	v_max_f32_e32 v182, 0, v182
	v_max_f32_e32 v183, 0, v183
	v_max_f32_e32 v184, 0, v184
	v_max_f32_e32 v185, 0, v185
	v_fmac_f32_e32 v110, v24, v182
	v_fmac_f32_e32 v111, v25, v183
	v_fmac_f32_e32 v112, v24, v184
	v_fmac_f32_e32 v113, v25, v185
	v_mfma_f32_16x16x32_bf16 v[198:201], v[90:93], v[74:77], v[198:201]
	v_max_f32_e32 v186, 0, v186
	v_max_f32_e32 v187, 0, v187
	v_max_f32_e32 v188, 0, v188
	v_max_f32_e32 v189, 0, v189
	v_fmac_f32_e32 v110, v106, v186
	v_fmac_f32_e32 v111, v107, v187
	v_fmac_f32_e32 v112, v106, v188
	v_fmac_f32_e32 v113, v107, v189
	v_mfma_f32_16x16x32_bf16 v[202:205], v[90:93], v[86:89], v[202:205]
	v_max_f32_e32 v190, 0, v190
	v_max_f32_e32 v191, 0, v191
	v_max_f32_e32 v192, 0, v192
	v_max_f32_e32 v193, 0, v193
	v_fmac_f32_e32 v110, v18, v190
	v_fmac_f32_e32 v111, v19, v191
	v_fmac_f32_e32 v112, v18, v192
	v_fmac_f32_e32 v113, v19, v193
	v_max_f32_e32 v198, 0, v198
	v_max_f32_e32 v199, 0, v199
	v_max_f32_e32 v200, 0, v200
	v_max_f32_e32 v201, 0, v201
	v_fmac_f32_e32 v110, v108, v198
	v_fmac_f32_e32 v111, v109, v199
	v_fmac_f32_e32 v112, v108, v200
	v_fmac_f32_e32 v113, v109, v201
	v_max_f32_e32 v202, 0, v202
	v_max_f32_e32 v203, 0, v203
	v_max_f32_e32 v204, 0, v204
	v_max_f32_e32 v205, 0, v205
	v_fmac_f32_e32 v110, v20, v202
	v_fmac_f32_e32 v111, v21, v203
	v_fmac_f32_e32 v112, v20, v204
	v_fmac_f32_e32 v113, v21, v205
	global_store_dwordx4 v[114:115], v[110:113], off
.LBB0_362:
	s_add_i32 s14, s13, 2
	s_cmp_ge_i32 s14, s7
	s_cbranch_scc1 .LBB0_359
	ds_read_b128 v[94:97], v119 offset:4608
	ds_read_b128 v[90:93], v119 offset:4672
	s_waitcnt lgkmcnt(1)
	v_mfma_f32_16x16x32_bf16 v[148:151], v[94:97], v[82:85], 0
	v_mfma_f32_16x16x32_bf16 v[156:159], v[94:97], v[30:33], 0
	v_mfma_f32_16x16x32_bf16 v[172:175], v[94:97], v[38:41], 0
	v_mfma_f32_16x16x32_bf16 v[182:185], v[94:97], v[46:49], 0
	v_mfma_f32_16x16x32_bf16 v[186:189], v[94:97], v[54:57], 0
	v_mfma_f32_16x16x32_bf16 v[190:193], v[94:97], v[62:65], 0
	v_mfma_f32_16x16x32_bf16 v[198:201], v[94:97], v[70:73], 0
	v_mfma_f32_16x16x32_bf16 v[202:205], v[94:97], v[78:81], 0
	s_waitcnt lgkmcnt(0)
	v_mfma_f32_16x16x32_bf16 v[148:151], v[90:93], v[26:29], v[148:151]
	v_mfma_f32_16x16x32_bf16 v[156:159], v[90:93], v[34:37], v[156:159]
	s_add_i32 s14, s10, s12
	s_add_i32 s14, s14, 32
	s_ashr_i32 s15, s14, 31
	v_lshl_add_u64 v[114:115], s[14:15], 2, v[100:101]
	v_mfma_f32_16x16x32_bf16 v[172:175], v[90:93], v[42:45], v[172:175]
	v_max_f32_e32 v148, 0, v148
	v_max_f32_e32 v149, 0, v149
	v_max_f32_e32 v150, 0, v150
	v_max_f32_e32 v151, 0, v151
	v_fma_f32 v110, v102, v148, 0
	v_fma_f32 v111, v103, v149, 0
	v_fma_f32 v112, v102, v150, 0
	v_fma_f32 v113, v103, v151, 0
	v_mfma_f32_16x16x32_bf16 v[182:185], v[90:93], v[50:53], v[182:185]
	v_max_f32_e32 v156, 0, v156
	v_max_f32_e32 v157, 0, v157
	v_max_f32_e32 v158, 0, v158
	v_max_f32_e32 v159, 0, v159
	v_fmac_f32_e32 v110, v22, v156
	v_fmac_f32_e32 v111, v23, v157
	v_fmac_f32_e32 v112, v22, v158
	v_fmac_f32_e32 v113, v23, v159
	v_mfma_f32_16x16x32_bf16 v[186:189], v[90:93], v[58:61], v[186:189]
	v_max_f32_e32 v172, 0, v172
	v_max_f32_e32 v173, 0, v173
	v_max_f32_e32 v174, 0, v174
	v_max_f32_e32 v175, 0, v175
	v_fmac_f32_e32 v110, v104, v172
	v_fmac_f32_e32 v111, v105, v173
	v_fmac_f32_e32 v112, v104, v174
	v_fmac_f32_e32 v113, v105, v175
	v_mfma_f32_16x16x32_bf16 v[190:193], v[90:93], v[66:69], v[190:193]
	v_max_f32_e32 v182, 0, v182
	v_max_f32_e32 v183, 0, v183
	v_max_f32_e32 v184, 0, v184
	v_max_f32_e32 v185, 0, v185
	v_fmac_f32_e32 v110, v24, v182
	v_fmac_f32_e32 v111, v25, v183
	v_fmac_f32_e32 v112, v24, v184
	v_fmac_f32_e32 v113, v25, v185
	v_mfma_f32_16x16x32_bf16 v[198:201], v[90:93], v[74:77], v[198:201]
	v_max_f32_e32 v186, 0, v186
	v_max_f32_e32 v187, 0, v187
	v_max_f32_e32 v188, 0, v188
	v_max_f32_e32 v189, 0, v189
	v_fmac_f32_e32 v110, v106, v186
	v_fmac_f32_e32 v111, v107, v187
	v_fmac_f32_e32 v112, v106, v188
	v_fmac_f32_e32 v113, v107, v189
	v_mfma_f32_16x16x32_bf16 v[202:205], v[90:93], v[86:89], v[202:205]
	v_max_f32_e32 v190, 0, v190
	v_max_f32_e32 v191, 0, v191
	v_max_f32_e32 v192, 0, v192
	v_max_f32_e32 v193, 0, v193
	v_fmac_f32_e32 v110, v18, v190
	v_fmac_f32_e32 v111, v19, v191
	v_fmac_f32_e32 v112, v18, v192
	v_fmac_f32_e32 v113, v19, v193
	v_max_f32_e32 v198, 0, v198
	v_max_f32_e32 v199, 0, v199
	v_max_f32_e32 v200, 0, v200
	v_max_f32_e32 v201, 0, v201
	v_fmac_f32_e32 v110, v108, v198
	v_fmac_f32_e32 v111, v109, v199
	v_fmac_f32_e32 v112, v108, v200
	v_fmac_f32_e32 v113, v109, v201
	v_max_f32_e32 v202, 0, v202
	v_max_f32_e32 v203, 0, v203
	v_max_f32_e32 v204, 0, v204
	v_max_f32_e32 v205, 0, v205
	v_fmac_f32_e32 v110, v20, v202
	v_fmac_f32_e32 v111, v21, v203
	v_fmac_f32_e32 v112, v20, v204
	v_fmac_f32_e32 v113, v21, v205
	global_store_dwordx4 v[114:115], v[110:113], off
	s_branch .LBB0_359
